# grid barrier: non-leader workgroups poll the top-level generation word directly instead of their XCD's generation word (one hop less on the release path)
# baseline (speedup 1.0000x reference)
; __device__ __forceinline__ unsigned xb_ld(unsigned* p)              { return __hip_atomic_load(p, __ATOMIC_RELAXED, __HIP_MEMORY_SCOPE_AGENT); }
; __device__ __forceinline__ unsigned xb_add(unsigned* p, unsigned v) { return __hip_atomic_fetch_add(p, v, __ATOMIC_RELAXED, __HIP_MEMORY_SCOPE_AGENT); }
; #define XB_SPIN(cond, bar) do { unsigned _sp = 0; while (cond) { __builtin_amdgcn_s_sleep(1); \
;     if ((++_sp & 255u) == 0u) { if (xb_ld(&(bar)[XB_TMO])) break; if (_sp > XB_SPIN_CAP) { atomicAdd(&(bar)[XB_TMO], 1u); break; } } } } while (0)
; __device__ __forceinline__ void xcd_barrier(const XcdBarrier& b) {
;     ...
;         const unsigned old = xb_add(&bar[XB_XSUB(b.x)], 1u);
;         const unsigned gen = old / nloc;
;         if (old + 1u == (gen + 1u) * nloc) {
;             __builtin_amdgcn_fence(__ATOMIC_RELEASE, "agent");
;             asm volatile("s_waitcnt vmcnt(0)" ::: "memory");
;             const unsigned og = xb_add(&bar[XB_TOP], 1u);
;             const unsigned tg = og / nx;
;             if (og + 1u == (tg + 1u) * nx) xb_add(&bar[XB_TOPGEN], 1u);
;             else XB_SPIN(xb_ld(&bar[XB_TOPGEN]) == tg, bar);
;             __builtin_amdgcn_fence(__ATOMIC_ACQUIRE, "agent");
;             xb_add(&bar[XB_XGEN(b.x)], 1u);
;             asm volatile("s_waitcnt vmcnt(0)" ::: "memory");
;         } else {
;             XB_SPIN(xb_ld(&bar[XB_XGEN(b.x)]) == gen, bar);
.LBB0_495:
	s_or_b64 exec, exec, s[26:27]
	v_cvt_f32_u32_e32 v5, v3
	s_waitcnt vmcnt(0)
	v_readfirstlane_b32 s2, v4
	v_sub_u32_e32 v4, 0, v3
	v_rcp_iflag_f32_e32 v5, v5
	v_add_u32_e32 v6, s2, v1
	v_mul_f32_e32 v5, 0x4f7ffffe, v5
	v_cvt_u32_f32_e32 v5, v5
	v_mul_lo_u32 v1, v4, v5
	v_mul_hi_u32 v1, v5, v1
	v_add_u32_e32 v1, v5, v1
	v_mul_hi_u32 v1, v6, v1
	v_mul_lo_u32 v4, v1, v3
	v_sub_u32_e32 v4, v6, v4
	v_add_u32_e32 v5, 1, v1
	v_cmp_ge_u32_e32 vcc, v4, v3
	s_nop 1
	v_cndmask_b32_e32 v1, v1, v5, vcc
	v_sub_u32_e32 v5, v4, v3
	v_cndmask_b32_e32 v4, v4, v5, vcc
	v_add_u32_e32 v5, 1, v1
	v_cmp_ge_u32_e32 vcc, v4, v3
	v_add_u32_e32 v4, 1, v6
	s_nop 0
	v_cndmask_b32_e32 v1, v1, v5, vcc
	v_mul_lo_u32 v5, v3, v1
	v_add_u32_e32 v3, v5, v3
	v_cmp_ne_u32_e32 vcc, v4, v3
	s_and_saveexec_b64 s[4:5], vcc
	s_xor_b64 s[26:27], exec, s[4:5]
	s_cbranch_execz .LBB0_509
	v_readlane_b32 s4, v254, 40
	v_readlane_b32 s5, v254, 41
	s_waitcnt lgkmcnt(0)
	s_nop 3
	global_load_dword v2, v0, s[4:5] sc1
	s_waitcnt vmcnt(0)
	v_cmp_eq_u32_e32 vcc, v2, v1
	s_and_saveexec_b64 s[40:41], vcc
	s_cbranch_execz .LBB0_508
	s_mov_b32 s4, 1
	s_mov_b64 s[42:43], 0
	s_branch .LBB0_499
